# adds counted lgkmcnt instead of mid-phase LDS drain in the P1 and P2-uq K-loops
# speedup vs baseline: 1.0115x; 1.0029x over previous
.LBB0_170:
	s_add_u32 s4, s0, 0xfffc0080
	s_addc_u32 s5, s1, -1
	s_add_i32 s83, 0, 0x10000
	s_cmp_eq_u32 s82, 12
	s_cselect_b32 s7, s2, s5
	s_cselect_b32 s6, s3, s4
	s_cselect_b32 s5, s75, s23
	s_cselect_b32 s4, s77, s22
	s_add_i32 s86, 0, 0x14000
	v_add_u32_e32 v142, s83, v213
	v_add_u32_e32 v168, s86, v213
	ds_read_b128 v[130:133], v142
	ds_read_b128 v[134:137], v142 offset:1024
	ds_read_b128 v[138:141], v142 offset:2048
	ds_read_b128 v[142:145], v142 offset:3072
	ds_read_b128 v[156:159], v168
	ds_read_b128 v[160:163], v168 offset:1024
	ds_read_b128 v[164:167], v168 offset:2048
	ds_read_b128 v[168:171], v168 offset:3072
	v_lshl_add_u64 v[180:181], s[0:1], 0, v[152:153]
	s_add_i32 m0, s35, 0xc000
	ds_read_b128 v[172:175], v214
	s_waitcnt lgkmcnt(6)
	ds_read_b128 v[184:187], v214 offset:1024
	ds_read_b128 v[188:191], v214 offset:2048
	ds_read_b128 v[192:195], v214 offset:3072
	ds_read_b128 v[200:203], v214 offset:4096
	ds_read_b128 v[216:219], v214 offset:5120
	ds_read_b128 v[220:223], v214 offset:6144
	ds_read_b128 v[224:227], v214 offset:7168
	global_load_lds_dwordx4 v[180:181], off
	v_lshl_add_u64 v[180:181], s[0:1], 0, v[154:155]
	s_add_i32 m0, s35, 0xe000
	s_nop 0
	global_load_lds_dwordx4 v[180:181], off
	s_waitcnt vmcnt(8)
	s_waitcnt lgkmcnt(0)
	s_barrier
	s_setprio 3
	s_waitcnt lgkmcnt(0)
	v_mfma_f32_16x16x32_bf16 v[126:129], v[130:133], v[172:175], v[126:129]
	v_mfma_f32_16x16x32_bf16 v[122:125], v[138:141], v[172:175], v[122:125]
	v_mfma_f32_16x16x32_bf16 v[110:113], v[130:133], v[188:191], v[110:113]
	v_mfma_f32_16x16x32_bf16 v[106:109], v[138:141], v[188:191], v[106:109]
	v_mfma_f32_16x16x32_bf16 v[94:97], v[130:133], v[200:203], v[94:97]
	v_mfma_f32_16x16x32_bf16 v[90:93], v[138:141], v[200:203], v[90:93]
	v_mfma_f32_16x16x32_bf16 v[78:81], v[130:133], v[220:223], v[78:81]
	v_mfma_f32_16x16x32_bf16 v[74:77], v[138:141], v[220:223], v[74:77]
	v_mfma_f32_16x16x32_bf16 v[126:129], v[134:137], v[184:187], v[126:129]
	v_mfma_f32_16x16x32_bf16 v[122:125], v[142:145], v[184:187], v[122:125]
	v_mfma_f32_16x16x32_bf16 v[110:113], v[134:137], v[192:195], v[110:113]
	v_mfma_f32_16x16x32_bf16 v[106:109], v[142:145], v[192:195], v[106:109]
	v_mfma_f32_16x16x32_bf16 v[94:97], v[134:137], v[216:219], v[94:97]
	v_mfma_f32_16x16x32_bf16 v[90:93], v[142:145], v[216:219], v[90:93]
	v_mfma_f32_16x16x32_bf16 v[78:81], v[134:137], v[224:227], v[78:81]
	v_mfma_f32_16x16x32_bf16 v[74:77], v[142:145], v[224:227], v[74:77]
	s_setprio 0
	s_setprio 3
	v_mfma_f32_16x16x32_bf16 v[118:121], v[156:159], v[172:175], v[118:121]
	v_mfma_f32_16x16x32_bf16 v[114:117], v[164:167], v[172:175], v[114:117]
	v_mfma_f32_16x16x32_bf16 v[102:105], v[156:159], v[188:191], v[102:105]
	v_mfma_f32_16x16x32_bf16 v[98:101], v[164:167], v[188:191], v[98:101]
	v_mfma_f32_16x16x32_bf16 v[86:89], v[156:159], v[200:203], v[86:89]
	v_mfma_f32_16x16x32_bf16 v[82:85], v[164:167], v[200:203], v[82:85]
	v_mfma_f32_16x16x32_bf16 v[70:73], v[156:159], v[220:223], v[70:73]
	v_mfma_f32_16x16x32_bf16 v[66:69], v[164:167], v[220:223], v[66:69]
	v_mfma_f32_16x16x32_bf16 v[118:121], v[160:163], v[184:187], v[118:121]
	v_mfma_f32_16x16x32_bf16 v[114:117], v[168:171], v[184:187], v[114:117]
	v_mfma_f32_16x16x32_bf16 v[102:105], v[160:163], v[192:195], v[102:105]
	v_mfma_f32_16x16x32_bf16 v[98:101], v[168:171], v[192:195], v[98:101]
	v_mfma_f32_16x16x32_bf16 v[86:89], v[160:163], v[216:219], v[86:89]
	v_mfma_f32_16x16x32_bf16 v[82:85], v[168:171], v[216:219], v[82:85]
	v_mfma_f32_16x16x32_bf16 v[70:73], v[160:163], v[224:227], v[70:73]
	v_mfma_f32_16x16x32_bf16 v[66:69], v[168:171], v[224:227], v[66:69]
	s_setprio 0
	s_barrier
	s_add_i32 s83, s83, s33
	v_lshl_add_u64 v[180:181], s[4:5], 0, v[0:1]
	s_mov_b32 m0, s83
	ds_read_b128 v[172:175], v214 offset:16384
	ds_read_b128 v[184:187], v214 offset:17408
	ds_read_b128 v[188:191], v214 offset:18432
	ds_read_b128 v[192:195], v214 offset:19456
	ds_read_b128 v[200:203], v214 offset:20480
	ds_read_b128 v[216:219], v214 offset:21504
	ds_read_b128 v[220:223], v214 offset:22528
	ds_read_b128 v[224:227], v214 offset:23552
	global_load_lds_dwordx4 v[180:181], off
	s_add_i32 m0, s83, 0x2000
	s_add_u32 s84, s4, 0x40000
	v_lshl_add_u64 v[182:183], s[4:5], 0, v[146:147]
	s_addc_u32 s85, s5, 0
	s_add_i32 s83, s86, s33
	global_load_lds_dwordx4 v[182:183], off
	v_lshl_add_u64 v[196:197], s[84:85], 0, v[0:1]
	s_mov_b32 m0, s83
	v_lshl_add_u64 v[198:199], s[6:7], 0, v[148:149]
	global_load_lds_dwordx4 v[196:197], off
	v_lshl_add_u64 v[196:197], s[84:85], 0, v[146:147]
	s_add_i32 m0, s83, 0x2000
	s_nop 0
	global_load_lds_dwordx4 v[196:197], off
	v_lshl_add_u64 v[196:197], s[6:7], 0, v[150:151]
	s_mov_b32 m0, s35
	s_nop 0
	global_load_lds_dwordx4 v[196:197], off
	s_mov_b32 m0, s36
	s_nop 0
	global_load_lds_dwordx4 v[198:199], off
	s_waitcnt vmcnt(8)
	s_waitcnt lgkmcnt(0)
	s_barrier
	s_setprio 3
	s_waitcnt lgkmcnt(0)
	v_mfma_f32_16x16x32_bf16 v[62:65], v[130:133], v[172:175], v[62:65]
	v_mfma_f32_16x16x32_bf16 v[58:61], v[138:141], v[172:175], v[58:61]
	v_mfma_f32_16x16x32_bf16 v[46:49], v[130:133], v[188:191], v[46:49]
	v_mfma_f32_16x16x32_bf16 v[42:45], v[138:141], v[188:191], v[42:45]
	v_mfma_f32_16x16x32_bf16 v[30:33], v[130:133], v[200:203], v[30:33]
	v_mfma_f32_16x16x32_bf16 v[26:29], v[138:141], v[200:203], v[26:29]
	v_mfma_f32_16x16x32_bf16 v[14:17], v[130:133], v[220:223], v[14:17]
	v_mfma_f32_16x16x32_bf16 v[10:13], v[138:141], v[220:223], v[10:13]
	v_mfma_f32_16x16x32_bf16 v[62:65], v[134:137], v[184:187], v[62:65]
	v_mfma_f32_16x16x32_bf16 v[58:61], v[142:145], v[184:187], v[58:61]
	v_mfma_f32_16x16x32_bf16 v[46:49], v[134:137], v[192:195], v[46:49]
	v_mfma_f32_16x16x32_bf16 v[42:45], v[142:145], v[192:195], v[42:45]
	v_mfma_f32_16x16x32_bf16 v[30:33], v[134:137], v[216:219], v[30:33]
	v_mfma_f32_16x16x32_bf16 v[26:29], v[142:145], v[216:219], v[26:29]
	v_mfma_f32_16x16x32_bf16 v[14:17], v[134:137], v[224:227], v[14:17]
	v_mfma_f32_16x16x32_bf16 v[10:13], v[142:145], v[224:227], v[10:13]
	s_setprio 0
	s_setprio 3
	v_mfma_f32_16x16x32_bf16 v[54:57], v[156:159], v[172:175], v[54:57]
	v_mfma_f32_16x16x32_bf16 v[50:53], v[164:167], v[172:175], v[50:53]
	v_mfma_f32_16x16x32_bf16 v[38:41], v[156:159], v[188:191], v[38:41]
	v_mfma_f32_16x16x32_bf16 v[34:37], v[164:167], v[188:191], v[34:37]
	v_mfma_f32_16x16x32_bf16 v[22:25], v[156:159], v[200:203], v[22:25]
	v_mfma_f32_16x16x32_bf16 v[18:21], v[164:167], v[200:203], v[18:21]
	v_mfma_f32_16x16x32_bf16 v[6:9], v[156:159], v[220:223], v[6:9]
	v_mfma_f32_16x16x32_bf16 v[2:5], v[164:167], v[220:223], v[2:5]
	v_mfma_f32_16x16x32_bf16 v[54:57], v[160:163], v[184:187], v[54:57]
	v_mfma_f32_16x16x32_bf16 v[50:53], v[168:171], v[184:187], v[50:53]
	v_mfma_f32_16x16x32_bf16 v[38:41], v[160:163], v[192:195], v[38:41]
	v_mfma_f32_16x16x32_bf16 v[34:37], v[168:171], v[192:195], v[34:37]
	v_mfma_f32_16x16x32_bf16 v[22:25], v[160:163], v[216:219], v[22:25]
	v_mfma_f32_16x16x32_bf16 v[18:21], v[168:171], v[216:219], v[18:21]
	v_mfma_f32_16x16x32_bf16 v[6:9], v[160:163], v[224:227], v[6:9]
	v_mfma_f32_16x16x32_bf16 v[2:5], v[168:171], v[224:227], v[2:5]
	s_setprio 0
	s_barrier
	s_add_i32 s83, 0, 0x18000
	s_add_i32 s84, 0, 0x1c000
	v_add_u32_e32 v142, s83, v213
	v_add_u32_e32 v168, s84, v213
	ds_read_b128 v[130:133], v142
	ds_read_b128 v[134:137], v142 offset:1024
	ds_read_b128 v[138:141], v142 offset:2048
	ds_read_b128 v[142:145], v142 offset:3072
	ds_read_b128 v[156:159], v168
	ds_read_b128 v[160:163], v168 offset:1024
	ds_read_b128 v[164:167], v168 offset:2048
	ds_read_b128 v[168:171], v168 offset:3072
	s_add_u32 s6, s6, 0x40000
	s_addc_u32 s7, s7, 0
	s_mov_b32 m0, s37
	v_lshl_add_u64 v[228:229], s[6:7], 0, v[150:151]
	ds_read_b128 v[172:175], v214 offset:32768
	ds_read_b128 v[184:187], v214 offset:33792
	ds_read_b128 v[188:191], v214 offset:34816
	ds_read_b128 v[192:195], v214 offset:35840
	ds_read_b128 v[200:203], v214 offset:36864
	ds_read_b128 v[216:219], v214 offset:37888
	ds_read_b128 v[220:223], v214 offset:38912
	ds_read_b128 v[224:227], v214 offset:39936
	global_load_lds_dwordx4 v[228:229], off
	v_lshl_add_u64 v[228:229], s[6:7], 0, v[148:149]
	s_mov_b32 m0, s96
	s_nop 0
	global_load_lds_dwordx4 v[228:229], off
	s_waitcnt vmcnt(8)
	s_waitcnt lgkmcnt(0)
	s_barrier
	s_setprio 3
	s_waitcnt lgkmcnt(0)
	v_mfma_f32_16x16x32_bf16 v[126:129], v[130:133], v[172:175], v[126:129]
	v_mfma_f32_16x16x32_bf16 v[122:125], v[138:141], v[172:175], v[122:125]
	v_mfma_f32_16x16x32_bf16 v[110:113], v[130:133], v[188:191], v[110:113]
	v_mfma_f32_16x16x32_bf16 v[106:109], v[138:141], v[188:191], v[106:109]
	v_mfma_f32_16x16x32_bf16 v[94:97], v[130:133], v[200:203], v[94:97]
	v_mfma_f32_16x16x32_bf16 v[90:93], v[138:141], v[200:203], v[90:93]
	v_mfma_f32_16x16x32_bf16 v[78:81], v[130:133], v[220:223], v[78:81]
	v_mfma_f32_16x16x32_bf16 v[74:77], v[138:141], v[220:223], v[74:77]
	v_mfma_f32_16x16x32_bf16 v[126:129], v[134:137], v[184:187], v[126:129]
	v_mfma_f32_16x16x32_bf16 v[122:125], v[142:145], v[184:187], v[122:125]
	v_mfma_f32_16x16x32_bf16 v[110:113], v[134:137], v[192:195], v[110:113]
	v_mfma_f32_16x16x32_bf16 v[106:109], v[142:145], v[192:195], v[106:109]
	v_mfma_f32_16x16x32_bf16 v[94:97], v[134:137], v[216:219], v[94:97]
	v_mfma_f32_16x16x32_bf16 v[90:93], v[142:145], v[216:219], v[90:93]
	v_mfma_f32_16x16x32_bf16 v[78:81], v[134:137], v[224:227], v[78:81]
	v_mfma_f32_16x16x32_bf16 v[74:77], v[142:145], v[224:227], v[74:77]
	s_setprio 0
	s_setprio 3
	v_mfma_f32_16x16x32_bf16 v[118:121], v[156:159], v[172:175], v[118:121]
	v_mfma_f32_16x16x32_bf16 v[114:117], v[164:167], v[172:175], v[114:117]
	v_mfma_f32_16x16x32_bf16 v[102:105], v[156:159], v[188:191], v[102:105]
	v_mfma_f32_16x16x32_bf16 v[98:101], v[164:167], v[188:191], v[98:101]
	v_mfma_f32_16x16x32_bf16 v[86:89], v[156:159], v[200:203], v[86:89]
	v_mfma_f32_16x16x32_bf16 v[82:85], v[164:167], v[200:203], v[82:85]
	v_mfma_f32_16x16x32_bf16 v[70:73], v[156:159], v[220:223], v[70:73]
	v_mfma_f32_16x16x32_bf16 v[66:69], v[164:167], v[220:223], v[66:69]
	v_mfma_f32_16x16x32_bf16 v[118:121], v[160:163], v[184:187], v[118:121]
	v_mfma_f32_16x16x32_bf16 v[114:117], v[168:171], v[184:187], v[114:117]
	v_mfma_f32_16x16x32_bf16 v[102:105], v[160:163], v[192:195], v[102:105]
	v_mfma_f32_16x16x32_bf16 v[98:101], v[168:171], v[192:195], v[98:101]
	v_mfma_f32_16x16x32_bf16 v[86:89], v[160:163], v[216:219], v[86:89]
	v_mfma_f32_16x16x32_bf16 v[82:85], v[168:171], v[216:219], v[82:85]
	v_mfma_f32_16x16x32_bf16 v[70:73], v[160:163], v[224:227], v[70:73]
	v_mfma_f32_16x16x32_bf16 v[66:69], v[168:171], v[224:227], v[66:69]
	s_setprio 0
	s_barrier
	s_add_i32 s6, s83, s33
	v_lshl_add_u64 v[180:181], v[180:181], 0, s[12:13]
	s_mov_b32 m0, s6
	ds_read_b128 v[172:175], v214 offset:49152
	ds_read_b128 v[184:187], v214 offset:50176
	ds_read_b128 v[188:191], v214 offset:51200
	ds_read_b128 v[192:195], v214 offset:52224
	ds_read_b128 v[200:203], v214 offset:53248
	ds_read_b128 v[216:219], v214 offset:54272
	ds_read_b128 v[220:223], v214 offset:55296
	ds_read_b128 v[224:227], v214 offset:56320
	global_load_lds_dwordx4 v[180:181], off
	s_add_i32 m0, s6, 0x2000
	s_add_u32 s4, s4, 0x40080
	v_lshl_add_u64 v[180:181], v[182:183], 0, s[12:13]
	s_addc_u32 s5, s5, 0
	s_add_i32 s6, s84, s33
	global_load_lds_dwordx4 v[180:181], off
	v_lshl_add_u64 v[180:181], s[4:5], 0, v[0:1]
	s_mov_b32 m0, s6
	s_nop 0
	global_load_lds_dwordx4 v[180:181], off
	v_lshl_add_u64 v[180:181], s[4:5], 0, v[146:147]
	s_add_i32 m0, s6, 0x2000
	s_nop 0
	global_load_lds_dwordx4 v[180:181], off
	v_lshl_add_u64 v[180:181], v[196:197], 0, s[12:13]
	s_mov_b32 m0, s25
	s_nop 0
	global_load_lds_dwordx4 v[180:181], off
	v_lshl_add_u64 v[180:181], v[198:199], 0, s[12:13]
	s_mov_b32 m0, s28
	s_nop 0
	global_load_lds_dwordx4 v[180:181], off
	s_waitcnt vmcnt(8)
	s_waitcnt lgkmcnt(0)
	s_barrier
	s_setprio 3
	s_waitcnt lgkmcnt(0)
	v_mfma_f32_16x16x32_bf16 v[62:65], v[130:133], v[172:175], v[62:65]
	v_mfma_f32_16x16x32_bf16 v[58:61], v[138:141], v[172:175], v[58:61]
	v_mfma_f32_16x16x32_bf16 v[46:49], v[130:133], v[188:191], v[46:49]
	v_mfma_f32_16x16x32_bf16 v[42:45], v[138:141], v[188:191], v[42:45]
	v_mfma_f32_16x16x32_bf16 v[30:33], v[130:133], v[200:203], v[30:33]
	v_mfma_f32_16x16x32_bf16 v[26:29], v[138:141], v[200:203], v[26:29]
	v_mfma_f32_16x16x32_bf16 v[14:17], v[130:133], v[220:223], v[14:17]
	v_mfma_f32_16x16x32_bf16 v[10:13], v[138:141], v[220:223], v[10:13]
	v_mfma_f32_16x16x32_bf16 v[62:65], v[134:137], v[184:187], v[62:65]
	v_mfma_f32_16x16x32_bf16 v[58:61], v[142:145], v[184:187], v[58:61]
	v_mfma_f32_16x16x32_bf16 v[46:49], v[134:137], v[192:195], v[46:49]
	v_mfma_f32_16x16x32_bf16 v[42:45], v[142:145], v[192:195], v[42:45]
	v_mfma_f32_16x16x32_bf16 v[30:33], v[134:137], v[216:219], v[30:33]
	v_mfma_f32_16x16x32_bf16 v[26:29], v[142:145], v[216:219], v[26:29]
	v_mfma_f32_16x16x32_bf16 v[14:17], v[134:137], v[224:227], v[14:17]
	v_mfma_f32_16x16x32_bf16 v[10:13], v[142:145], v[224:227], v[10:13]
	s_setprio 0
	s_setprio 3
	v_mfma_f32_16x16x32_bf16 v[54:57], v[156:159], v[172:175], v[54:57]
	v_mfma_f32_16x16x32_bf16 v[50:53], v[164:167], v[172:175], v[50:53]
	v_mfma_f32_16x16x32_bf16 v[38:41], v[156:159], v[188:191], v[38:41]
	v_mfma_f32_16x16x32_bf16 v[34:37], v[164:167], v[188:191], v[34:37]
	v_mfma_f32_16x16x32_bf16 v[22:25], v[156:159], v[200:203], v[22:25]
	v_mfma_f32_16x16x32_bf16 v[18:21], v[164:167], v[200:203], v[18:21]
	v_mfma_f32_16x16x32_bf16 v[6:9], v[156:159], v[220:223], v[6:9]
	v_mfma_f32_16x16x32_bf16 v[2:5], v[164:167], v[220:223], v[2:5]
	v_mfma_f32_16x16x32_bf16 v[54:57], v[160:163], v[184:187], v[54:57]
	v_mfma_f32_16x16x32_bf16 v[50:53], v[168:171], v[184:187], v[50:53]
	v_mfma_f32_16x16x32_bf16 v[38:41], v[160:163], v[192:195], v[38:41]
	v_mfma_f32_16x16x32_bf16 v[34:37], v[168:171], v[192:195], v[34:37]
	v_mfma_f32_16x16x32_bf16 v[22:25], v[160:163], v[216:219], v[22:25]
	v_mfma_f32_16x16x32_bf16 v[18:21], v[168:171], v[216:219], v[18:21]
	v_mfma_f32_16x16x32_bf16 v[6:9], v[160:163], v[224:227], v[6:9]
	v_mfma_f32_16x16x32_bf16 v[2:5], v[168:171], v[224:227], v[2:5]
	s_setprio 0
	s_barrier
	s_add_i32 s82, s82, 2
	s_add_u32 s0, s0, 0x100
	s_addc_u32 s1, s1, 0
	s_add_u32 s22, s22, 0x100
	s_addc_u32 s23, s23, 0
	s_cmp_gt_u32 s82, 13
	s_cbranch_scc0 .LBB0_170
	v_readlane_b32 s0, v254, 6
	v_readlane_b32 s1, v254, 7
	s_and_b64 vcc, exec, s[0:1]
	s_cbranch_vccz .LBB0_173
	s_barrier

.LBB0_371:
	s_add_u32 s4, s0, 0x100
	s_addc_u32 s5, s1, 0
	s_add_i32 s49, 0, 0x10000
	s_cmp_eq_u32 s48, 2
	s_cselect_b32 s25, s39, s5
	s_cselect_b32 s24, s38, s4
	s_cselect_b32 s23, s47, s3
	s_cselect_b32 s22, s46, s2
	s_add_i32 s56, 0, 0x14000
	v_add_u32_e32 v142, s49, v197
	v_add_u32_e32 v168, s56, v197
	ds_read_b128 v[130:133], v142
	ds_read_b128 v[134:137], v142 offset:1024
	ds_read_b128 v[138:141], v142 offset:2048
	ds_read_b128 v[142:145], v142 offset:3072
	ds_read_b128 v[156:159], v168
	s_waitcnt lgkmcnt(4)
	ds_read_b128 v[160:163], v168 offset:1024
	ds_read_b128 v[164:167], v168 offset:2048
	ds_read_b128 v[168:171], v168 offset:3072
	v_lshl_add_u64 v[180:181], s[0:1], 0, v[152:153]
	s_add_i32 m0, s29, 0xc000
	ds_read_b128 v[172:175], v198
	ds_read_b128 v[184:187], v198 offset:1024
	ds_read_b128 v[188:191], v198 offset:2048
	ds_read_b128 v[200:203], v198 offset:3072
	ds_read_b128 v[212:215], v198 offset:4096
	ds_read_b128 v[216:219], v198 offset:5120
	ds_read_b128 v[220:223], v198 offset:6144
	ds_read_b128 v[224:227], v198 offset:7168
	global_load_lds_dwordx4 v[180:181], off
	v_lshl_add_u64 v[180:181], s[0:1], 0, v[154:155]
	s_add_i32 m0, s29, 0xe000
	s_nop 0
	global_load_lds_dwordx4 v[180:181], off
	s_waitcnt vmcnt(8)
	s_waitcnt lgkmcnt(0)
	s_barrier
	s_setprio 3
	s_waitcnt lgkmcnt(0)
	v_mfma_f32_16x16x32_bf16 v[118:121], v[130:133], v[172:175], v[118:121]
	v_mfma_f32_16x16x32_bf16 v[126:129], v[138:141], v[172:175], v[126:129]
	v_mfma_f32_16x16x32_bf16 v[106:109], v[130:133], v[188:191], v[106:109]
	v_mfma_f32_16x16x32_bf16 v[110:113], v[138:141], v[188:191], v[110:113]
	v_mfma_f32_16x16x32_bf16 v[90:93], v[130:133], v[212:215], v[90:93]
	v_mfma_f32_16x16x32_bf16 v[94:97], v[138:141], v[212:215], v[94:97]
	v_mfma_f32_16x16x32_bf16 v[74:77], v[130:133], v[220:223], v[74:77]
	v_mfma_f32_16x16x32_bf16 v[78:81], v[138:141], v[220:223], v[78:81]
	v_mfma_f32_16x16x32_bf16 v[118:121], v[134:137], v[184:187], v[118:121]
	v_mfma_f32_16x16x32_bf16 v[126:129], v[142:145], v[184:187], v[126:129]
	v_mfma_f32_16x16x32_bf16 v[106:109], v[134:137], v[200:203], v[106:109]
	v_mfma_f32_16x16x32_bf16 v[110:113], v[142:145], v[200:203], v[110:113]
	v_mfma_f32_16x16x32_bf16 v[90:93], v[134:137], v[216:219], v[90:93]
	v_mfma_f32_16x16x32_bf16 v[94:97], v[142:145], v[216:219], v[94:97]
	v_mfma_f32_16x16x32_bf16 v[74:77], v[134:137], v[224:227], v[74:77]
	v_mfma_f32_16x16x32_bf16 v[78:81], v[142:145], v[224:227], v[78:81]
	s_setprio 0
	s_setprio 3
	v_mfma_f32_16x16x32_bf16 v[114:117], v[156:159], v[172:175], v[114:117]
	v_mfma_f32_16x16x32_bf16 v[122:125], v[164:167], v[172:175], v[122:125]
	v_mfma_f32_16x16x32_bf16 v[98:101], v[156:159], v[188:191], v[98:101]
	v_mfma_f32_16x16x32_bf16 v[102:105], v[164:167], v[188:191], v[102:105]
	v_mfma_f32_16x16x32_bf16 v[82:85], v[156:159], v[212:215], v[82:85]
	v_mfma_f32_16x16x32_bf16 v[86:89], v[164:167], v[212:215], v[86:89]
	v_mfma_f32_16x16x32_bf16 v[66:69], v[156:159], v[220:223], v[66:69]
	v_mfma_f32_16x16x32_bf16 v[70:73], v[164:167], v[220:223], v[70:73]
	v_mfma_f32_16x16x32_bf16 v[114:117], v[160:163], v[184:187], v[114:117]
	v_mfma_f32_16x16x32_bf16 v[122:125], v[168:171], v[184:187], v[122:125]
	v_mfma_f32_16x16x32_bf16 v[98:101], v[160:163], v[200:203], v[98:101]
	v_mfma_f32_16x16x32_bf16 v[102:105], v[168:171], v[200:203], v[102:105]
	v_mfma_f32_16x16x32_bf16 v[82:85], v[160:163], v[216:219], v[82:85]
	v_mfma_f32_16x16x32_bf16 v[86:89], v[168:171], v[216:219], v[86:89]
	v_mfma_f32_16x16x32_bf16 v[66:69], v[160:163], v[224:227], v[66:69]
	v_mfma_f32_16x16x32_bf16 v[70:73], v[168:171], v[224:227], v[70:73]
	s_setprio 0
	s_barrier
	s_add_i32 s0, s49, s33
	v_lshl_add_u64 v[180:181], s[22:23], 0, v[0:1]
	s_mov_b32 m0, s0
	ds_read_b128 v[172:175], v198 offset:16384
	ds_read_b128 v[184:187], v198 offset:17408
	ds_read_b128 v[188:191], v198 offset:18432
	ds_read_b128 v[200:203], v198 offset:19456
	ds_read_b128 v[212:215], v198 offset:20480
	ds_read_b128 v[216:219], v198 offset:21504
	ds_read_b128 v[220:223], v198 offset:22528
	ds_read_b128 v[224:227], v198 offset:23552
	global_load_lds_dwordx4 v[180:181], off
	s_add_i32 m0, s0, 0x2000
	s_add_u32 s0, s22, 0x18000
	v_lshl_add_u64 v[182:183], s[22:23], 0, v[146:147]
	s_addc_u32 s1, s23, 0
	s_add_i32 s49, s56, s33
	global_load_lds_dwordx4 v[182:183], off
	v_lshl_add_u64 v[192:193], s[0:1], 0, v[0:1]
	s_mov_b32 m0, s49
	v_lshl_add_u64 v[228:229], s[24:25], 0, v[148:149]
	global_load_lds_dwordx4 v[192:193], off
	v_lshl_add_u64 v[192:193], s[0:1], 0, v[146:147]
	s_add_i32 m0, s49, 0x2000
	s_nop 0
	global_load_lds_dwordx4 v[192:193], off
	v_lshl_add_u64 v[192:193], s[24:25], 0, v[150:151]
	s_mov_b32 m0, s29
	s_nop 0
	global_load_lds_dwordx4 v[192:193], off
	s_mov_b32 m0, s30
	s_nop 0
	global_load_lds_dwordx4 v[228:229], off
	s_waitcnt vmcnt(8)
	s_waitcnt lgkmcnt(0)
	s_barrier
	s_setprio 3
	s_waitcnt lgkmcnt(0)
	v_mfma_f32_16x16x32_bf16 v[58:61], v[130:133], v[172:175], v[58:61]
	v_mfma_f32_16x16x32_bf16 v[62:65], v[138:141], v[172:175], v[62:65]
	v_mfma_f32_16x16x32_bf16 v[42:45], v[130:133], v[188:191], v[42:45]
	v_mfma_f32_16x16x32_bf16 v[46:49], v[138:141], v[188:191], v[46:49]
	v_mfma_f32_16x16x32_bf16 v[26:29], v[130:133], v[212:215], v[26:29]
	v_mfma_f32_16x16x32_bf16 v[30:33], v[138:141], v[212:215], v[30:33]
	v_mfma_f32_16x16x32_bf16 v[10:13], v[130:133], v[220:223], v[10:13]
	v_mfma_f32_16x16x32_bf16 v[14:17], v[138:141], v[220:223], v[14:17]
	v_mfma_f32_16x16x32_bf16 v[58:61], v[134:137], v[184:187], v[58:61]
	v_mfma_f32_16x16x32_bf16 v[62:65], v[142:145], v[184:187], v[62:65]
	v_mfma_f32_16x16x32_bf16 v[42:45], v[134:137], v[200:203], v[42:45]
	v_mfma_f32_16x16x32_bf16 v[46:49], v[142:145], v[200:203], v[46:49]
	v_mfma_f32_16x16x32_bf16 v[26:29], v[134:137], v[216:219], v[26:29]
	v_mfma_f32_16x16x32_bf16 v[30:33], v[142:145], v[216:219], v[30:33]
	v_mfma_f32_16x16x32_bf16 v[10:13], v[134:137], v[224:227], v[10:13]
	v_mfma_f32_16x16x32_bf16 v[14:17], v[142:145], v[224:227], v[14:17]
	s_setprio 0
	s_setprio 3
	v_mfma_f32_16x16x32_bf16 v[50:53], v[156:159], v[172:175], v[50:53]
	v_mfma_f32_16x16x32_bf16 v[54:57], v[164:167], v[172:175], v[54:57]
	v_mfma_f32_16x16x32_bf16 v[34:37], v[156:159], v[188:191], v[34:37]
	v_mfma_f32_16x16x32_bf16 v[38:41], v[164:167], v[188:191], v[38:41]
	v_mfma_f32_16x16x32_bf16 v[18:21], v[156:159], v[212:215], v[18:21]
	v_mfma_f32_16x16x32_bf16 v[22:25], v[164:167], v[212:215], v[22:25]
	v_mfma_f32_16x16x32_bf16 v[2:5], v[156:159], v[220:223], v[2:5]
	v_mfma_f32_16x16x32_bf16 v[6:9], v[164:167], v[220:223], v[6:9]
	v_mfma_f32_16x16x32_bf16 v[50:53], v[160:163], v[184:187], v[50:53]
	v_mfma_f32_16x16x32_bf16 v[54:57], v[168:171], v[184:187], v[54:57]
	v_mfma_f32_16x16x32_bf16 v[34:37], v[160:163], v[200:203], v[34:37]
	v_mfma_f32_16x16x32_bf16 v[38:41], v[168:171], v[200:203], v[38:41]
	v_mfma_f32_16x16x32_bf16 v[18:21], v[160:163], v[216:219], v[18:21]
	v_mfma_f32_16x16x32_bf16 v[22:25], v[168:171], v[216:219], v[22:25]
	v_mfma_f32_16x16x32_bf16 v[2:5], v[160:163], v[224:227], v[2:5]
	v_mfma_f32_16x16x32_bf16 v[6:9], v[168:171], v[224:227], v[6:9]
	s_setprio 0
	s_barrier
	s_add_i32 s49, 0, 0x18000
	s_add_i32 s56, 0, 0x1c000
	v_add_u32_e32 v142, s49, v197
	v_add_u32_e32 v168, s56, v197
	ds_read_b128 v[130:133], v142
	ds_read_b128 v[134:137], v142 offset:1024
	ds_read_b128 v[138:141], v142 offset:2048
	ds_read_b128 v[142:145], v142 offset:3072
	ds_read_b128 v[156:159], v168
	ds_read_b128 v[160:163], v168 offset:1024
	ds_read_b128 v[164:167], v168 offset:2048
	ds_read_b128 v[168:171], v168 offset:3072
	s_add_u32 s0, s24, 0x18000
	s_addc_u32 s1, s25, 0
	s_mov_b32 m0, s31
	v_lshl_add_u64 v[230:231], s[0:1], 0, v[150:151]
	ds_read_b128 v[172:175], v198 offset:32768
	ds_read_b128 v[184:187], v198 offset:33792
	ds_read_b128 v[188:191], v198 offset:34816
	ds_read_b128 v[200:203], v198 offset:35840
	ds_read_b128 v[212:215], v198 offset:36864
	ds_read_b128 v[216:219], v198 offset:37888
	ds_read_b128 v[220:223], v198 offset:38912
	ds_read_b128 v[224:227], v198 offset:39936
	global_load_lds_dwordx4 v[230:231], off
	v_lshl_add_u64 v[230:231], s[0:1], 0, v[148:149]
	s_mov_b32 m0, s35
	s_nop 0
	global_load_lds_dwordx4 v[230:231], off
	s_waitcnt vmcnt(8)
	s_waitcnt lgkmcnt(0)
	s_barrier
	s_setprio 3
	s_waitcnt lgkmcnt(0)
	v_mfma_f32_16x16x32_bf16 v[118:121], v[130:133], v[172:175], v[118:121]
	v_mfma_f32_16x16x32_bf16 v[126:129], v[138:141], v[172:175], v[126:129]
	v_mfma_f32_16x16x32_bf16 v[106:109], v[130:133], v[188:191], v[106:109]
	v_mfma_f32_16x16x32_bf16 v[110:113], v[138:141], v[188:191], v[110:113]
	v_mfma_f32_16x16x32_bf16 v[90:93], v[130:133], v[212:215], v[90:93]
	v_mfma_f32_16x16x32_bf16 v[94:97], v[138:141], v[212:215], v[94:97]
	v_mfma_f32_16x16x32_bf16 v[74:77], v[130:133], v[220:223], v[74:77]
	v_mfma_f32_16x16x32_bf16 v[78:81], v[138:141], v[220:223], v[78:81]
	v_mfma_f32_16x16x32_bf16 v[118:121], v[134:137], v[184:187], v[118:121]
	v_mfma_f32_16x16x32_bf16 v[126:129], v[142:145], v[184:187], v[126:129]
	v_mfma_f32_16x16x32_bf16 v[106:109], v[134:137], v[200:203], v[106:109]
	v_mfma_f32_16x16x32_bf16 v[110:113], v[142:145], v[200:203], v[110:113]
	v_mfma_f32_16x16x32_bf16 v[90:93], v[134:137], v[216:219], v[90:93]
	v_mfma_f32_16x16x32_bf16 v[94:97], v[142:145], v[216:219], v[94:97]
	v_mfma_f32_16x16x32_bf16 v[74:77], v[134:137], v[224:227], v[74:77]
	v_mfma_f32_16x16x32_bf16 v[78:81], v[142:145], v[224:227], v[78:81]
	s_setprio 0
	s_setprio 3
	v_mfma_f32_16x16x32_bf16 v[114:117], v[156:159], v[172:175], v[114:117]
	v_mfma_f32_16x16x32_bf16 v[122:125], v[164:167], v[172:175], v[122:125]
	v_mfma_f32_16x16x32_bf16 v[98:101], v[156:159], v[188:191], v[98:101]
	v_mfma_f32_16x16x32_bf16 v[102:105], v[164:167], v[188:191], v[102:105]
	v_mfma_f32_16x16x32_bf16 v[82:85], v[156:159], v[212:215], v[82:85]
	v_mfma_f32_16x16x32_bf16 v[86:89], v[164:167], v[212:215], v[86:89]
	v_mfma_f32_16x16x32_bf16 v[66:69], v[156:159], v[220:223], v[66:69]
	v_mfma_f32_16x16x32_bf16 v[70:73], v[164:167], v[220:223], v[70:73]
	v_mfma_f32_16x16x32_bf16 v[114:117], v[160:163], v[184:187], v[114:117]
	v_mfma_f32_16x16x32_bf16 v[122:125], v[168:171], v[184:187], v[122:125]
	v_mfma_f32_16x16x32_bf16 v[98:101], v[160:163], v[200:203], v[98:101]
	v_mfma_f32_16x16x32_bf16 v[102:105], v[168:171], v[200:203], v[102:105]
	v_mfma_f32_16x16x32_bf16 v[82:85], v[160:163], v[216:219], v[82:85]
	v_mfma_f32_16x16x32_bf16 v[86:89], v[168:171], v[216:219], v[86:89]
	v_mfma_f32_16x16x32_bf16 v[66:69], v[160:163], v[224:227], v[66:69]
	v_mfma_f32_16x16x32_bf16 v[70:73], v[168:171], v[224:227], v[70:73]
	s_setprio 0
	s_barrier
	s_add_i32 s0, s49, s33
	v_lshl_add_u64 v[180:181], v[180:181], 0, s[12:13]
	s_mov_b32 m0, s0
	ds_read_b128 v[172:175], v198 offset:49152
	ds_read_b128 v[184:187], v198 offset:50176
	ds_read_b128 v[188:191], v198 offset:51200
	ds_read_b128 v[200:203], v198 offset:52224
	ds_read_b128 v[212:215], v198 offset:53248
	ds_read_b128 v[216:219], v198 offset:54272
	ds_read_b128 v[220:223], v198 offset:55296
	ds_read_b128 v[224:227], v198 offset:56320
	global_load_lds_dwordx4 v[180:181], off
	s_add_i32 m0, s0, 0x2000
	s_add_u32 s0, s22, 0x18080
	v_lshl_add_u64 v[180:181], v[182:183], 0, s[12:13]
	s_addc_u32 s1, s23, 0
	s_add_i32 s22, s56, s33
	global_load_lds_dwordx4 v[180:181], off
	v_lshl_add_u64 v[180:181], s[0:1], 0, v[0:1]
	s_mov_b32 m0, s22
	s_nop 0
	global_load_lds_dwordx4 v[180:181], off
	v_lshl_add_u64 v[180:181], s[0:1], 0, v[146:147]
	s_add_i32 m0, s22, 0x2000
	s_nop 0
	global_load_lds_dwordx4 v[180:181], off
	v_lshl_add_u64 v[180:181], v[192:193], 0, s[12:13]
	s_mov_b32 m0, s51
	s_nop 0
	global_load_lds_dwordx4 v[180:181], off
	v_lshl_add_u64 v[180:181], v[228:229], 0, s[12:13]
	s_mov_b32 m0, s52
	s_nop 0
	global_load_lds_dwordx4 v[180:181], off
	s_waitcnt vmcnt(8)
	s_waitcnt lgkmcnt(0)
	s_barrier
	s_setprio 3
	s_waitcnt lgkmcnt(0)
	v_mfma_f32_16x16x32_bf16 v[58:61], v[130:133], v[172:175], v[58:61]
	v_mfma_f32_16x16x32_bf16 v[62:65], v[138:141], v[172:175], v[62:65]
	v_mfma_f32_16x16x32_bf16 v[42:45], v[130:133], v[188:191], v[42:45]
	v_mfma_f32_16x16x32_bf16 v[46:49], v[138:141], v[188:191], v[46:49]
	v_mfma_f32_16x16x32_bf16 v[26:29], v[130:133], v[212:215], v[26:29]
	v_mfma_f32_16x16x32_bf16 v[30:33], v[138:141], v[212:215], v[30:33]
	v_mfma_f32_16x16x32_bf16 v[10:13], v[130:133], v[220:223], v[10:13]
	v_mfma_f32_16x16x32_bf16 v[14:17], v[138:141], v[220:223], v[14:17]
	v_mfma_f32_16x16x32_bf16 v[58:61], v[134:137], v[184:187], v[58:61]
	v_mfma_f32_16x16x32_bf16 v[62:65], v[142:145], v[184:187], v[62:65]
	v_mfma_f32_16x16x32_bf16 v[42:45], v[134:137], v[200:203], v[42:45]
	v_mfma_f32_16x16x32_bf16 v[46:49], v[142:145], v[200:203], v[46:49]
	v_mfma_f32_16x16x32_bf16 v[26:29], v[134:137], v[216:219], v[26:29]
	v_mfma_f32_16x16x32_bf16 v[30:33], v[142:145], v[216:219], v[30:33]
	v_mfma_f32_16x16x32_bf16 v[10:13], v[134:137], v[224:227], v[10:13]
	v_mfma_f32_16x16x32_bf16 v[14:17], v[142:145], v[224:227], v[14:17]
	s_setprio 0
	s_setprio 3
	v_mfma_f32_16x16x32_bf16 v[50:53], v[156:159], v[172:175], v[50:53]
	v_mfma_f32_16x16x32_bf16 v[54:57], v[164:167], v[172:175], v[54:57]
	v_mfma_f32_16x16x32_bf16 v[34:37], v[156:159], v[188:191], v[34:37]
	v_mfma_f32_16x16x32_bf16 v[38:41], v[164:167], v[188:191], v[38:41]
	v_mfma_f32_16x16x32_bf16 v[18:21], v[156:159], v[212:215], v[18:21]
	v_mfma_f32_16x16x32_bf16 v[22:25], v[164:167], v[212:215], v[22:25]
	v_mfma_f32_16x16x32_bf16 v[2:5], v[156:159], v[220:223], v[2:5]
	v_mfma_f32_16x16x32_bf16 v[6:9], v[164:167], v[220:223], v[6:9]
	v_mfma_f32_16x16x32_bf16 v[50:53], v[160:163], v[184:187], v[50:53]
	v_mfma_f32_16x16x32_bf16 v[54:57], v[168:171], v[184:187], v[54:57]
	v_mfma_f32_16x16x32_bf16 v[34:37], v[160:163], v[200:203], v[34:37]
	v_mfma_f32_16x16x32_bf16 v[38:41], v[168:171], v[200:203], v[38:41]
	v_mfma_f32_16x16x32_bf16 v[18:21], v[160:163], v[216:219], v[18:21]
	v_mfma_f32_16x16x32_bf16 v[22:25], v[168:171], v[216:219], v[22:25]
	v_mfma_f32_16x16x32_bf16 v[2:5], v[160:163], v[224:227], v[2:5]
	v_mfma_f32_16x16x32_bf16 v[6:9], v[168:171], v[224:227], v[6:9]
	s_setprio 0
	s_barrier
	s_add_i32 s48, s48, 2
	s_add_u32 s2, s2, 0x100
	s_addc_u32 s3, s3, 0
	s_cmp_gt_u32 s48, 3
	s_mov_b64 s[0:1], s[4:5]
	s_cbranch_scc0 .LBB0_371
	v_readlane_b32 s0, v254, 6
	v_readlane_b32 s1, v254, 7
	s_and_b64 vcc, exec, s[0:1]
	s_cbranch_vccz .LBB0_374
	s_barrier
